# v28 + s5_local Horner chains: packed FMAs with register shuffles replaced by scalar v_fma_f32 on the MFMA outputs (28 fewer VALU per chunk, bit-identical)
# baseline (speedup 1.0000x reference)
; template <int DIR>
; __device__ __forceinline__ void s5_local_dir(const bf16_t* UZ, unsigned char* ws, int gw, int NGW, int lane) {
;     ...
; #pragma unroll
;         for (int t = 0; t < 4; ++t) {
;             f32x4 cr = {0.f, 0.f, 0.f, 0.f}, ci = {0.f, 0.f, 0.f, 0.f};
; #pragma unroll
;             for (int m = 0; m < 4; ++m) {
;                 cr = __builtin_amdgcn_mfma_f32_16x16x16bf16_1k(Uf[m], Bre[m][t], cr, 0, 0, 0);
;                 ci = __builtin_amdgcn_mfma_f32_16x16x16bf16_1k(Uf[m], Bim[m][t], ci, 0, 0, 0);
;             }
;             f32x2 s2 = {DIR ? cr[3] : cr[0], DIR ? ci[3] : ci[0]};
; #pragma unroll
;             for (int ii = 1; ii < 4; ++ii) { const int i = DIR ? 3 - ii : ii;
;                 s2 = cmac(s2, (f32x2){a1r[t], a1r[t]}, (f32x2){-a1i[t], a1i[t]}, (f32x2){cr[i], ci[i]}); }
;             s2 = cmac(s2, (f32x2){wr_[t], wr_[t]}, (f32x2){-wi_[t], wi_[t]}, (f32x2){0.f, 0.f});
;             float sr = s2.x, si = s2.y;
;             sr += __shfl_xor(sr, 16); si += __shfl_xor(si, 16); sr += __shfl_xor(sr, 32); si += __shfl_xor(si, 32);
;             if (fq == 0) { e[16 * t + fr] = Rr[t]; e[64 + 16 * t + fr] = Ri[t]; }
;             const float nr = fmaf(a64r[t], Rr[t], fmaf(-a64i[t], Ri[t], sr)), ni = fmaf(a64r[t], Ri[t], fmaf(a64i[t], Rr[t], si)); Rr[t] = nr; Ri[t] = ni;
;         }
.Lp7_d0_st:
	s_or_b64 exec, exec, s[38:39]
	s_waitcnt vmcnt(15)
	v_mfma_f32_16x16x16_bf16 v[140:143], v[110:111], v[26:27], 0
	v_mfma_f32_16x16x16_bf16 v[144:147], v[110:111], v[28:29], 0
	s_waitcnt vmcnt(14)
	v_mfma_f32_16x16x16_bf16 v[140:143], v[112:113], v[30:31], v[140:143]
	v_mfma_f32_16x16x16_bf16 v[144:147], v[112:113], v[32:33], v[144:147]
	s_waitcnt vmcnt(13)
	v_mfma_f32_16x16x16_bf16 v[140:143], v[114:115], v[34:35], v[140:143]
	v_mfma_f32_16x16x16_bf16 v[144:147], v[114:115], v[36:37], v[144:147]
	s_waitcnt vmcnt(12)
	v_mfma_f32_16x16x16_bf16 v[140:143], v[108:109], v[38:39], v[140:143]
	v_mfma_f32_16x16x16_bf16 v[144:147], v[108:109], v[40:41], v[144:147]
	v_mfma_f32_16x16x16_bf16 v[196:199], v[110:111], v[48:49], 0
	v_mfma_f32_16x16x16_bf16 v[200:203], v[110:111], v[50:51], 0
	v_mfma_f32_16x16x16_bf16 v[196:199], v[112:113], v[52:53], v[196:199]
	v_mfma_f32_16x16x16_bf16 v[200:203], v[112:113], v[54:55], v[200:203]
	v_mfma_f32_16x16x16_bf16 v[196:199], v[114:115], v[56:57], v[196:199]
	v_mfma_f32_16x16x16_bf16 v[200:203], v[114:115], v[58:59], v[200:203]
	v_mfma_f32_16x16x16_bf16 v[196:199], v[108:109], v[60:61], v[196:199]
	v_mfma_f32_16x16x16_bf16 v[200:203], v[108:109], v[62:63], v[200:203]
	v_mfma_f32_16x16x16_bf16 v[208:211], v[110:111], v[70:71], 0
	v_mfma_f32_16x16x16_bf16 v[212:215], v[110:111], v[72:73], 0
	v_mfma_f32_16x16x16_bf16 v[208:211], v[112:113], v[74:75], v[208:211]
	v_mfma_f32_16x16x16_bf16 v[212:215], v[112:113], v[76:77], v[212:215]
	v_mfma_f32_16x16x16_bf16 v[208:211], v[114:115], v[78:79], v[208:211]
	v_mfma_f32_16x16x16_bf16 v[212:215], v[114:115], v[80:81], v[212:215]
	v_mfma_f32_16x16x16_bf16 v[208:211], v[108:109], v[82:83], v[208:211]
	v_mfma_f32_16x16x16_bf16 v[212:215], v[108:109], v[84:85], v[212:215]
	v_mfma_f32_16x16x16_bf16 v[228:231], v[110:111], v[92:93], 0
	v_mfma_f32_16x16x16_bf16 v[232:235], v[110:111], v[94:95], 0
	v_mfma_f32_16x16x16_bf16 v[228:231], v[112:113], v[96:97], v[228:231]
	v_mfma_f32_16x16x16_bf16 v[186:189], v[112:113], v[98:99], v[232:235]
	v_mfma_f32_16x16x16_bf16 v[228:231], v[114:115], v[100:101], v[228:231]
	v_mfma_f32_16x16x16_bf16 v[186:189], v[114:115], v[102:103], v[186:189]
	v_mfma_f32_16x16x16_bf16 v[228:231], v[108:109], v[104:105], v[228:231]
	v_mfma_f32_16x16x16_bf16 v[184:187], v[108:109], v[106:107], v[186:189]
	s_nop 6
	v_fma_f32 v148, v20, v143, v142
	v_fma_f32 v204, v42, v199, v198
	v_fma_f32 v216, v64, v211, v210
	v_fma_f32 v188, v86, v231, v230
	v_fma_f32 v149, v21, v147, v146
	v_fma_f32 v205, v43, v203, v202
	v_fma_f32 v217, v65, v215, v214
	v_fma_f32 v189, v87, v187, v186
	v_fma_f32 v142, v0, v147, v148
	v_fma_f32 v198, v4, v203, v204
	v_fma_f32 v210, v8, v215, v216
	v_fma_f32 v186, v12, v187, v188
	v_fma_f32 v143, v1, v143, v149
	v_fma_f32 v199, v5, v199, v205
	v_fma_f32 v211, v9, v211, v217
	v_fma_f32 v187, v13, v231, v189
	v_fma_f32 v146, v20, v142, v141
	v_fma_f32 v202, v42, v198, v197
	v_fma_f32 v214, v64, v210, v209
	v_fma_f32 v188, v86, v186, v229
	v_fma_f32 v147, v21, v143, v145
	v_fma_f32 v203, v43, v199, v201
	v_fma_f32 v215, v65, v211, v213
	v_fma_f32 v189, v87, v187, v185
	v_fma_f32 v160, v0, v143, v146
	v_fma_f32 v167, v4, v199, v202
	v_fma_f32 v236, v8, v211, v214
	v_fma_f32 v243, v12, v187, v188
	v_fma_f32 v143, v1, v142, v147
	v_fma_f32 v199, v5, v198, v203
	v_fma_f32 v211, v9, v210, v215
	v_fma_f32 v187, v13, v186, v189
	v_fma_f32 v140, v20, v160, v140
	v_fma_f32 v196, v42, v167, v196
	v_fma_f32 v208, v64, v236, v208
	v_fma_f32 v244, v86, v243, v228
	v_fma_f32 v141, v21, v143, v144
	v_fma_f32 v197, v43, v199, v200
	v_fma_f32 v209, v65, v211, v212
	v_fma_f32 v185, v87, v187, v184
	v_fma_f32 v140, v0, v143, v140
	v_fma_f32 v196, v4, v199, v196
	v_fma_f32 v208, v8, v211, v208
	v_fma_f32 v184, v12, v187, v244
	v_fma_f32 v141, v1, v160, v141
	v_fma_f32 v197, v5, v167, v197
	v_fma_f32 v209, v9, v236, v209
	v_fma_f32 v185, v13, v243, v185
	v_fma_f32 v142, v22, v140, 0
	v_fma_f32 v198, v44, v196, 0
	v_fma_f32 v210, v66, v208, 0
	v_fma_f32 v186, v88, v184, 0
	v_fma_f32 v143, v23, v141, 0
	v_fma_f32 v199, v45, v197, 0
	v_fma_f32 v211, v67, v209, 0
	v_fma_f32 v187, v89, v185, 0
	v_fma_f32 v160, v24, v141, v142
	v_fma_f32 v167, v46, v197, v198
	v_fma_f32 v236, v68, v209, v210
	v_fma_f32 v243, v90, v185, v186
	v_fma_f32 v141, v25, v140, v143
	v_fma_f32 v197, v47, v196, v199
	v_fma_f32 v209, v69, v208, v211
	v_fma_f32 v185, v91, v184, v187
	ds_bpermute_b32 v142, v131, v160
	ds_bpermute_b32 v143, v131, v141
	ds_bpermute_b32 v198, v131, v167
	ds_bpermute_b32 v199, v131, v197
	ds_bpermute_b32 v210, v131, v236
	ds_bpermute_b32 v211, v131, v209
	ds_bpermute_b32 v186, v131, v243
	ds_bpermute_b32 v187, v131, v185
	s_waitcnt lgkmcnt(0)
	v_add_f32_e32 v140, v160, v142
	v_add_f32_e32 v141, v141, v143
	v_add_f32_e32 v196, v167, v198
	v_add_f32_e32 v197, v197, v199
	v_add_f32_e32 v208, v236, v210
	v_add_f32_e32 v209, v209, v211
	v_add_f32_e32 v189, v243, v186
	v_add_f32_e32 v191, v185, v187
	ds_bpermute_b32 v142, v132, v140
	ds_bpermute_b32 v143, v132, v141
	ds_bpermute_b32 v198, v132, v196
	ds_bpermute_b32 v199, v132, v197
	ds_bpermute_b32 v210, v132, v208
	ds_bpermute_b32 v211, v132, v209
	ds_bpermute_b32 v228, v132, v189
	ds_bpermute_b32 v229, v132, v191
	s_waitcnt lgkmcnt(0)
	v_add_f32_e32 v109, v140, v142
	v_add_f32_e32 v108, v141, v143
	v_fma_f32 v110, -v3, v139, v109
	v_fmac_f32_e32 v110, v2, v17
	v_fmac_f32_e32 v108, v3, v17
	v_add_f32_e32 v17, v196, v198
	v_fma_f32 v112, -v7, v138, v17
	v_add_f32_e32 v17, v208, v210
	v_add_f32_e32 v109, v197, v199
	v_add_f32_e32 v111, v209, v211
	v_fma_f32 v114, -v11, v136, v17
	v_add_f32_e32 v17, v189, v228
	v_add_f32_e32 v113, v191, v229
	v_fmac_f32_e32 v109, v7, v137
	v_fmac_f32_e32 v111, v11, v135
	v_fma_f32 v115, -v15, v134, v17
	v_fmac_f32_e32 v113, v15, v133
	v_fmac_f32_e32 v108, v2, v139
	v_fmac_f32_e32 v112, v6, v137
	v_fmac_f32_e32 v109, v6, v138
	v_fmac_f32_e32 v114, v10, v135
	v_fmac_f32_e32 v111, v10, v136
	v_fmac_f32_e32 v115, v14, v133
	v_fmac_f32_e32 v113, v14, v134
	v_lshl_add_u64 v[116:117], v[116:117], 0, s[2:3]
	v_subrev_u32_e32 v16, 64, v16
	s_and_b64 vcc, exec, s[36:37]
	s_cbranch_vccnz .LBB0_684
	s_mov_b32 s38, s49
	v_mov_b32_e32 v17, v110
	v_mov_b32_e32 v137, v112
	v_mov_b32_e32 v135, v114
	v_mov_b32_e32 v133, v115
	v_mov_b32_e32 v139, v108
	v_mov_b32_e32 v138, v109
	v_mov_b32_e32 v136, v111
	v_mov_b32_e32 v134, v113
	s_waitcnt vmcnt(3)
	v_mov_b32_e32 v110, v118
	v_mov_b32_e32 v111, v119
	s_waitcnt vmcnt(2)
	v_mov_b32_e32 v112, v120
	v_mov_b32_e32 v113, v121
	s_waitcnt vmcnt(1)
	v_mov_b32_e32 v114, v122
	v_mov_b32_e32 v115, v123
	s_waitcnt vmcnt(0)
	v_mov_b32_e32 v108, v124
	v_mov_b32_e32 v109, v125
	s_branch .LBB0_649

; template <int DIR>
; __device__ __forceinline__ void s5_local_dir(const bf16_t* UZ, unsigned char* ws, int gw, int NGW, int lane) {
;     ...
; #pragma unroll
;         for (int t = 0; t < 4; ++t) {
;             f32x4 cr = {0.f, 0.f, 0.f, 0.f}, ci = {0.f, 0.f, 0.f, 0.f};
; #pragma unroll
;             for (int m = 0; m < 4; ++m) {
;                 cr = __builtin_amdgcn_mfma_f32_16x16x16bf16_1k(Uf[m], Bre[m][t], cr, 0, 0, 0);
;                 ci = __builtin_amdgcn_mfma_f32_16x16x16bf16_1k(Uf[m], Bim[m][t], ci, 0, 0, 0);
;             }
;             f32x2 s2 = {DIR ? cr[3] : cr[0], DIR ? ci[3] : ci[0]};
; #pragma unroll
;             for (int ii = 1; ii < 4; ++ii) { const int i = DIR ? 3 - ii : ii;
;                 s2 = cmac(s2, (f32x2){a1r[t], a1r[t]}, (f32x2){-a1i[t], a1i[t]}, (f32x2){cr[i], ci[i]}); }
;             s2 = cmac(s2, (f32x2){wr_[t], wr_[t]}, (f32x2){-wi_[t], wi_[t]}, (f32x2){0.f, 0.f});
;             float sr = s2.x, si = s2.y;
;             sr += __shfl_xor(sr, 16); si += __shfl_xor(si, 16); sr += __shfl_xor(sr, 32); si += __shfl_xor(si, 32);
;             if (fq == 0) { e[16 * t + fr] = Rr[t]; e[64 + 16 * t + fr] = Ri[t]; }
;             const float nr = fmaf(a64r[t], Rr[t], fmaf(-a64i[t], Ri[t], sr)), ni = fmaf(a64r[t], Ri[t], fmaf(a64i[t], Rr[t], si)); Rr[t] = nr; Ri[t] = ni;
;         }
.Lp7_d1_st:
	s_or_b64 exec, exec, s[24:25]
	s_waitcnt vmcnt(15)
	v_mfma_f32_16x16x16_bf16 v[136:139], v[108:109], v[26:27], 0
	v_mfma_f32_16x16x16_bf16 v[140:143], v[108:109], v[28:29], 0
	s_waitcnt vmcnt(14)
	v_mfma_f32_16x16x16_bf16 v[136:139], v[112:113], v[30:31], v[136:139]
	v_mfma_f32_16x16x16_bf16 v[140:143], v[112:113], v[32:33], v[140:143]
	s_waitcnt vmcnt(13)
	v_mfma_f32_16x16x16_bf16 v[136:139], v[114:115], v[34:35], v[136:139]
	v_mfma_f32_16x16x16_bf16 v[140:143], v[114:115], v[36:37], v[140:143]
	s_waitcnt vmcnt(12)
	v_mfma_f32_16x16x16_bf16 v[136:139], v[110:111], v[38:39], v[136:139]
	v_mfma_f32_16x16x16_bf16 v[140:143], v[110:111], v[40:41], v[140:143]
	v_mfma_f32_16x16x16_bf16 v[196:199], v[108:109], v[48:49], 0
	v_mfma_f32_16x16x16_bf16 v[200:203], v[108:109], v[50:51], 0
	v_mfma_f32_16x16x16_bf16 v[196:199], v[112:113], v[52:53], v[196:199]
	v_mfma_f32_16x16x16_bf16 v[200:203], v[112:113], v[54:55], v[200:203]
	v_mfma_f32_16x16x16_bf16 v[196:199], v[114:115], v[56:57], v[196:199]
	v_mfma_f32_16x16x16_bf16 v[200:203], v[114:115], v[58:59], v[200:203]
	v_mfma_f32_16x16x16_bf16 v[196:199], v[110:111], v[60:61], v[196:199]
	v_mfma_f32_16x16x16_bf16 v[200:203], v[110:111], v[62:63], v[200:203]
	v_mfma_f32_16x16x16_bf16 v[208:211], v[108:109], v[70:71], 0
	v_mfma_f32_16x16x16_bf16 v[212:215], v[108:109], v[72:73], 0
	v_mfma_f32_16x16x16_bf16 v[208:211], v[112:113], v[74:75], v[208:211]
	v_mfma_f32_16x16x16_bf16 v[212:215], v[112:113], v[76:77], v[212:215]
	v_mfma_f32_16x16x16_bf16 v[208:211], v[114:115], v[78:79], v[208:211]
	v_mfma_f32_16x16x16_bf16 v[212:215], v[114:115], v[80:81], v[212:215]
	v_mfma_f32_16x16x16_bf16 v[208:211], v[110:111], v[82:83], v[208:211]
	v_mfma_f32_16x16x16_bf16 v[212:215], v[110:111], v[84:85], v[212:215]
	v_mfma_f32_16x16x16_bf16 v[224:227], v[108:109], v[88:89], 0
	v_mfma_f32_16x16x16_bf16 v[228:231], v[108:109], v[90:91], 0
	v_mfma_f32_16x16x16_bf16 v[224:227], v[112:113], v[96:97], v[224:227]
	v_mfma_f32_16x16x16_bf16 v[228:231], v[112:113], v[98:99], v[228:231]
	v_mfma_f32_16x16x16_bf16 v[224:227], v[114:115], v[100:101], v[224:227]
	v_mfma_f32_16x16x16_bf16 v[188:191], v[114:115], v[102:103], v[228:231]
	v_mfma_f32_16x16x16_bf16 v[224:227], v[110:111], v[104:105], v[224:227]
	v_mfma_f32_16x16x16_bf16 v[184:187], v[110:111], v[106:107], v[188:191]
	s_nop 6
	v_fma_f32 v144, v18, v136, v137
	v_fma_f32 v204, v42, v196, v197
	v_fma_f32 v216, v64, v208, v209
	v_fma_f32 v188, v86, v224, v225
	v_fma_f32 v145, v19, v140, v141
	v_fma_f32 v205, v43, v200, v201
	v_fma_f32 v217, v65, v212, v213
	v_fma_f32 v189, v87, v184, v185
	v_fma_f32 v160, v0, v140, v144
	v_fma_f32 v167, v4, v200, v204
	v_fma_f32 v236, v8, v212, v216
	v_fma_f32 v184, v12, v184, v188
	v_fma_f32 v137, v1, v136, v145
	v_fma_f32 v197, v5, v196, v205
	v_fma_f32 v209, v9, v208, v217
	v_fma_f32 v185, v13, v224, v189
	v_fma_f32 v140, v18, v160, v138
	v_fma_f32 v200, v42, v167, v198
	v_fma_f32 v212, v64, v236, v210
	v_fma_f32 v188, v86, v184, v226
	v_fma_f32 v141, v19, v137, v142
	v_fma_f32 v201, v43, v197, v202
	v_fma_f32 v213, v65, v209, v214
	v_fma_f32 v189, v87, v185, v186
	v_fma_f32 v136, v0, v137, v140
	v_fma_f32 v196, v4, v197, v200
	v_fma_f32 v208, v8, v209, v212
	v_fma_f32 v243, v12, v185, v188
	v_fma_f32 v137, v1, v160, v141
	v_fma_f32 v197, v5, v167, v201
	v_fma_f32 v209, v9, v236, v213
	v_fma_f32 v185, v13, v184, v189
	v_fma_f32 v138, v18, v136, v139
	v_fma_f32 v198, v42, v196, v199
	v_fma_f32 v210, v64, v208, v211
	v_fma_f32 v186, v86, v243, v227
	v_fma_f32 v139, v19, v137, v143
	v_fma_f32 v199, v43, v197, v203
	v_fma_f32 v211, v65, v209, v215
	v_fma_f32 v187, v87, v185, v187
	v_fma_f32 v160, v0, v137, v138
	v_fma_f32 v167, v4, v197, v198
	v_fma_f32 v236, v8, v209, v210
	v_fma_f32 v184, v12, v185, v186
	v_fma_f32 v137, v1, v136, v139
	v_fma_f32 v197, v5, v196, v199
	v_fma_f32 v209, v9, v208, v211
	v_fma_f32 v185, v13, v243, v187
	v_fma_f32 v138, v22, v160, 0
	v_fma_f32 v198, v44, v167, 0
	v_fma_f32 v210, v66, v236, 0
	v_fma_f32 v186, v92, v184, 0
	v_fma_f32 v139, v23, v137, 0
	v_fma_f32 v199, v45, v197, 0
	v_fma_f32 v211, v67, v209, 0
	v_fma_f32 v187, v93, v185, 0
	v_fma_f32 v136, v24, v137, v138
	v_fma_f32 v196, v46, v197, v198
	v_fma_f32 v208, v68, v209, v210
	v_fma_f32 v243, v94, v185, v186
	v_fma_f32 v137, v25, v160, v139
	v_fma_f32 v197, v47, v167, v199
	v_fma_f32 v209, v69, v236, v211
	v_fma_f32 v185, v95, v184, v187
	ds_bpermute_b32 v138, v128, v136
	ds_bpermute_b32 v139, v128, v137
	ds_bpermute_b32 v198, v128, v196
	ds_bpermute_b32 v199, v128, v197
	ds_bpermute_b32 v210, v128, v208
	ds_bpermute_b32 v211, v128, v209
	ds_bpermute_b32 v186, v128, v243
	ds_bpermute_b32 v187, v128, v185
	s_waitcnt lgkmcnt(0)
	v_add_f32_e32 v136, v136, v138
	v_add_f32_e32 v137, v137, v139
	v_add_f32_e32 v196, v196, v198
	v_add_f32_e32 v197, v197, v199
	v_add_f32_e32 v208, v208, v210
	v_add_f32_e32 v209, v209, v211
	v_add_f32_e32 v189, v243, v186
	v_add_f32_e32 v191, v185, v187
	ds_bpermute_b32 v138, v129, v136
	ds_bpermute_b32 v139, v129, v137
	ds_bpermute_b32 v198, v129, v196
	ds_bpermute_b32 v199, v129, v197
	ds_bpermute_b32 v210, v129, v208
	ds_bpermute_b32 v211, v129, v209
	ds_bpermute_b32 v224, v129, v189
	ds_bpermute_b32 v225, v129, v191
	s_waitcnt lgkmcnt(0)
	v_add_f32_e32 v109, v136, v138
	v_add_f32_e32 v108, v137, v139
	v_fma_f32 v110, -v3, v135, v109
	v_fmac_f32_e32 v110, v2, v21
	v_fmac_f32_e32 v108, v3, v21
	v_add_f32_e32 v21, v196, v198
	v_fma_f32 v112, -v7, v134, v21
	v_add_f32_e32 v21, v208, v210
	v_add_f32_e32 v109, v197, v199
	v_add_f32_e32 v111, v209, v211
	v_fma_f32 v114, -v11, v132, v21
	v_add_f32_e32 v21, v189, v224
	v_add_f32_e32 v113, v191, v225
	v_fmac_f32_e32 v109, v7, v133
	v_fmac_f32_e32 v111, v11, v131
	v_fma_f32 v115, -v15, v130, v21
	v_fmac_f32_e32 v113, v15, v127
	v_fmac_f32_e32 v108, v2, v135
	v_fmac_f32_e32 v112, v6, v133
	v_fmac_f32_e32 v109, v6, v134
	v_fmac_f32_e32 v114, v10, v131
	v_fmac_f32_e32 v111, v10, v132
	v_fmac_f32_e32 v115, v14, v127
	v_fmac_f32_e32 v113, v14, v130
	v_lshl_add_u64 v[116:117], v[116:117], 0, s[4:5]
	v_add_u32_e32 v20, 64, v20
	s_and_b64 vcc, exec, s[22:23]
	s_cbranch_vccnz .LBB0_702
	s_mov_b32 s24, s40
	v_mov_b32_e32 v21, v110
	v_mov_b32_e32 v133, v112
	v_mov_b32_e32 v131, v114
	v_mov_b32_e32 v127, v115
	v_mov_b32_e32 v135, v108
	v_mov_b32_e32 v134, v109
	v_mov_b32_e32 v132, v111
	v_mov_b32_e32 v130, v113
	s_waitcnt vmcnt(3)
	v_mov_b32_e32 v108, v118
	v_mov_b32_e32 v109, v119
	s_waitcnt vmcnt(2)
	v_mov_b32_e32 v112, v120
	v_mov_b32_e32 v113, v121
	s_waitcnt vmcnt(1)
	v_mov_b32_e32 v114, v122
	v_mov_b32_e32 v115, v123
	s_waitcnt vmcnt(0)
	v_mov_b32_e32 v110, v124
	v_mov_b32_e32 v111, v125
	s_branch .LBB0_671
